# SSD chunk loops: transposed x tile (Xt) 16-B chunks XOR-swizzled by (row>>3)&3 so the 2-byte transpose stores are 2-way instead of 8-way bank conflicted
# speedup vs baseline: 1.0039x; 1.0039x over previous
; DI int opaque_tid() { int t = threadIdx.x; asm volatile("" : "+v"(t)); return t; }
; template <int PROBE>
; PH void ssd_prompt_item(const Params& p, int layer, int b, int e, int seg) {
;   const int tid = opaque_tid(), lane = tid & 63, w = tid >> 6, quad = lane >> 4, l15 = lane & 15;
;   float* SEND = (float*)(p.ws + WS_SEND) + (size_t)((layer * 96 + b * 12 + e) * NSEG) * 8192;
;   unsigned* SFLAG = (unsigned*)(p.ws + WS_SFLAG) + (layer * 96 + b * 12 + e) * NSEG;
;   f32x4 h[8];
; #pragma unroll
;   for (int i = 0; i < 8; ++i) h[i] = (f32x4){0.f, 0.f, 0.f, 0.f};
;   float dtot = 0.f;
;   const size_t eoff = (size_t)(w * 16 + l15) * 128 + quad * 4;
;   if (seg < NSEG - 1) ssd_chunk_loop<PROBE, 1, 10>(p, layer, b, e, seg * 10, h, dtot, false);
; __global__ void __launch_bounds__(256, 2) mega(Params p) {
;     ...
;         if (it < 384) { const int v = it % 96; ssd_prompt_item<0>(p, layer, v / 12, v % 12, it / 96); }
.LBB0_477:
	s_setprio 3
	s_mul_hi_i32 s0, s84, 0x2aaaaaab
	s_lshr_b32 s1, s0, 31
	s_ashr_i32 s0, s0, 4
	s_add_i32 s86, s0, s1
	s_mul_i32 s0, s86, 0x60
	s_sub_i32 s0, s84, s0
	s_mul_i32 s1, s0, 43
	s_sext_i32_i16 s2, s1
	s_ashr_i32 s2, s2, 9
	s_bfe_u32 s1, s1, 0x1000f
	s_add_i32 s1, s2, s1
	s_sext_i32_i16 s25, s1
	s_mul_i32 s1, s1, 12
	s_sub_i32 s24, s0, s1
	v_readlane_b32 s6, v255, 50
	s_sext_i32_i8 s15, s24
	s_mul_i32 s2, s6, 0x60
	s_add_i32 s2, s2, s15
	s_cmpk_lt_i32 s84, 0xc0
	s_cselect_b64 s[48:49], -1, 0
	s_cmpk_gt_i32 s84, 0xbf
	s_cselect_b64 s[8:9], -1, 0
	v_mov_b32_e32 v174, v182
	s_and_b64 vcc, exec, s[8:9]
	s_mul_i32 s21, s86, 0x280
	s_mul_i32 s19, s86, 10
	s_cbranch_vccnz .LBB0_485
; template <int PROBE, int SONLY, int CPS>
; DI void ssd_chunk_loop(const Params& p, int layer, int b, int e, int c0, f32x4 (&h)[8], float& dtot, bool write_final) {
;     ...
;     for (int i = 0; i < 2; ++i) {
;       const int idx = tid + 256 * i, r = idx >> 3, c8 = idx & 7;
;       const float dtv = dt_s[r];
;       float f[8]; unpack8v(xr[i], f);
; #pragma unroll
;       for (int j = 0; j < 8; ++j) Xt[(c8 * 8 + j) * 72 + r] = f2bf(f[j] * dtv);
;     }
;     ...
;         const bf16x8 xf = ldfrag(Xt, 72, w * 16, ks * 32, lane);
	s_bfe_i32 s0, s24, 0x80000
	s_mul_i32 s0, s0, 43
	s_bfe_u32 s1, s0, 0x1000f
	s_bfe_u32 s0, s0, 0x80008
	s_add_i32 s13, s0, s1
	s_mul_i32 s0, s6, 0xffffffac
	s_add_i32 s0, s2, s0
	s_ashr_i32 s1, s0, 31
	v_readlane_b32 s52, v252, 37
	s_lshl_b64 s[6:7], s[0:1], 2
	v_readlane_b32 s60, v252, 45
	v_readlane_b32 s61, v252, 46
	s_add_u32 s0, s60, s6
	v_readlane_b32 s62, v252, 47
	s_addc_u32 s1, s61, s7
	v_readlane_b32 s63, v252, 48
	s_add_u32 s6, s62, s6
	s_waitcnt vmcnt(2)
	v_mov_b32_e32 v22, v182
	s_addc_u32 s7, s63, s7
	global_load_dword v23, v161, s[6:7]
	global_load_dword v79, v161, s[0:1]
	v_readlane_b32 s50, v254, 18
	s_waitcnt vmcnt(6)
	v_add_u32_e32 v7, 0x100, v22
	s_waitcnt vmcnt(4)
	v_add_u32_e32 v8, 0x200, v22
	v_add_u32_e32 v9, 0x300, v22
	s_sext_i32_i8 s18, s13
	s_lshl_b32 s13, s25, 11
	v_readlane_b32 s51, v254, 19
	v_ashrrev_i32_e32 v73, 4, v22
	v_lshlrev_b32_e32 v6, 4, v22
	v_ashrrev_i32_e32 v75, 4, v7
	v_ashrrev_i32_e32 v76, 4, v8
	v_ashrrev_i32_e32 v77, 4, v9
	s_lshl_b32 s22, s18, 7
	s_lshl_b32 s36, s15, 6
	s_add_i32 s18, s13, s21
	v_mov_b32_e32 v0, s24
	v_mov_b64_e32 v[2:3], s[50:51]
	v_and_b32_e32 v72, 63, v22
	v_and_b32_e32 v160, 0xf0, v6
	s_ashr_i32 s23, s22, 31
	s_ashr_i32 s37, s36, 31
	v_add_u32_e32 v6, s18, v73
	v_add_u32_e32 v8, s18, v75
	v_add_u32_e32 v10, s18, v76
	s_waitcnt vmcnt(2)
	v_add_u32_e32 v12, s18, v77
	v_mov_b64_e32 v[4:5], s[4:5]
	v_bfe_i32 v64, v0, 0, 8
	v_lshlrev_b32_e32 v0, 3, v22
	v_ashrrev_i32_e32 v78, 3, v7
	s_lshl_b64 s[0:1], s[22:23], 1
	s_lshl_b64 s[22:23], s[36:37], 1
	v_or_b32_e32 v13, s18, v72
	v_mad_i64_i32 v[6:7], s[36:37], v6, s34, v[2:3]
	v_mad_i64_i32 v[8:9], s[36:37], v8, s34, v[2:3]
	v_mad_i64_i32 v[10:11], s[36:37], v10, s34, v[2:3]
	v_mad_i64_i32 v[2:3], s[36:37], v12, s34, v[2:3]
	v_ashrrev_i32_e32 v65, 31, v64
	v_and_b32_e32 v33, 56, v0
	s_add_u32 s22, s50, s22
	v_mad_i64_i32 v[4:5], s[36:37], v13, s97, v[4:5]
	v_lshl_add_u64 v[6:7], v[6:7], 0, s[0:1]
	v_lshl_add_u64 v[8:9], v[8:9], 0, s[0:1]
	v_lshl_add_u64 v[10:11], v[10:11], 0, s[0:1]
	v_lshl_add_u64 v[2:3], v[2:3], 0, s[0:1]
	s_waitcnt lgkmcnt(0)
	v_mov_b32_e32 v1, v161
	v_ashrrev_i32_e32 v74, 3, v22
	v_lshlrev_b32_e32 v0, 1, v33
	s_addc_u32 s23, s51, s23
	v_lshl_add_u64 v[16:17], v[64:65], 1, v[4:5]
	v_lshl_add_u64 v[4:5], v[6:7], 0, v[160:161]
	v_lshl_add_u64 v[6:7], v[8:9], 0, v[160:161]
	v_lshl_add_u64 v[8:9], v[10:11], 0, v[160:161]
	v_lshl_add_u64 v[12:13], v[2:3], 0, v[160:161]
	v_add_u32_e32 v18, s18, v74
	v_lshl_add_u64 v[66:67], s[22:23], 0, v[0:1]
	global_load_dwordx4 v[0:3], v[4:5], off offset:1536
	s_nop 0
	global_load_dwordx4 v[4:7], v[6:7], off offset:1536
	s_nop 0
	global_load_dwordx4 v[8:11], v[8:9], off offset:1536
	s_nop 0
	global_load_dwordx4 v[12:15], v[12:13], off offset:1536
	v_add_co_u32_e32 v16, vcc, s16, v16
	v_add_u32_e32 v20, s18, v78
	v_mad_i64_i32 v[18:19], s[22:23], v18, s34, v[66:67]
	v_addc_co_u32_e32 v17, vcc, 0, v17, vcc
	v_mad_i64_i32 v[20:21], s[22:23], v20, s34, v[66:67]
	global_load_dwordx4 v[28:31], v[18:19], off
	global_load_dwordx4 v[24:27], v[20:21], off
	global_load_ushort v95, v[16:17], off offset:1536
	v_ashrrev_i32_e32 v32, 6, v22
	v_and_b32_e32 v16, 48, v22
	v_add_u32_e32 v17, 32, v160
	v_add_u32_e32 v16, 32, v16
	s_mul_i32 s6, s86, 10
	s_add_i32 s18, s6, 10
	s_waitcnt vmcnt(8)
	v_mul_f32_e32 v18, 0x3fb8aa3b, v23
	v_and_b32_e32 v23, 15, v22
	v_lshl_or_b32 v34, v32, 4, v23
	v_mad_u64_u32 v[68:69], s[22:23], v34, s11, v[16:17]
	v_exp_f32_e32 v80, v18
	v_lshlrev_b32_e32 v18, 2, v72
	v_readlane_b32 s22, v255, 27
	s_movk_i32 s36, 0x110
	v_mad_u32_u24 v19, v72, s36, 32
	v_add_u32_e32 v69, s22, v18
	v_lshl_add_u32 v82, v74, 2, s22
	v_lshl_add_u32 v83, v78, 2, s22
	s_movk_i32 s22, 0x1200
	v_mul_i32_i24_e32 v21, 0xfffffef2, v72
	v_mul_lo_u32 v32, v32, s22
	s_add_u32 s0, s50, s0
	v_cmp_gt_u32_e32 vcc, 64, v22
	v_add_u32_e32 v81, s17, v18
	v_and_b32_e32 v20, 0xffffffc0, v22
	v_mul_u32_u24_e32 v18, 0x90, v23
	v_mul_lo_u32 v22, v73, s36
	v_mul_lo_u32 v23, v75, s36
	v_mul_lo_u32 v89, v76, s36
	v_mul_lo_u32 v90, v77, s36
	v_lshl_add_u32 v91, v74, 1, 32
	v_mul_u32_u24_e32 v92, 0x90, v33
	v_lshl_add_u32 v93, v78, 1, 32
	v_add3_u32 v84, v19, v21, v32
	v_lshlrev_b32_e32 v21, 1, v72
	s_addc_u32 s1, s51, s1
	s_mov_b32 s7, 0
	v_cmp_eq_u32_e64 s[36:37], 0, v72
	v_cmp_gt_u32_e64 s[38:39], 2, v72
	v_cmp_gt_u32_e64 s[40:41], 4, v72
	v_cmp_gt_u32_e64 s[42:43], 8, v72
	v_cmp_gt_u32_e64 s[44:45], 16, v72
	v_cmp_gt_u32_e64 s[46:47], 32, v72
	v_add3_u32 v85, 32, v32, v21
	v_lshl_add_u64 v[70:71], s[0:1], 0, v[160:161]
	v_mov_b32_e32 v86, 0
	v_mov_b32_e32 v60, 0
	v_mov_b32_e32 v61, 0
	v_mov_b32_e32 v62, 0
	v_mov_b32_e32 v63, 0
	v_mov_b32_e32 v56, 0
	v_mov_b32_e32 v57, 0
	v_mov_b32_e32 v58, 0
	v_mov_b32_e32 v59, 0
	v_mov_b32_e32 v52, 0
	v_mov_b32_e32 v53, 0
	v_mov_b32_e32 v54, 0
	v_mov_b32_e32 v55, 0
	v_mov_b32_e32 v48, 0
	v_mov_b32_e32 v49, 0
	v_mov_b32_e32 v50, 0
	v_mov_b32_e32 v51, 0
	v_mov_b32_e32 v44, 0
	v_mov_b32_e32 v45, 0
	v_mov_b32_e32 v46, 0
	v_mov_b32_e32 v47, 0
	v_mov_b32_e32 v36, 0
	v_mov_b32_e32 v37, 0
	v_mov_b32_e32 v38, 0
	v_mov_b32_e32 v39, 0
	v_mov_b32_e32 v40, 0
	v_mov_b32_e32 v41, 0
	v_mov_b32_e32 v42, 0
	v_mov_b32_e32 v43, 0
	v_mov_b32_e32 v32, 0
	v_mov_b32_e32 v33, 0
	v_mov_b32_e32 v34, 0
	v_mov_b32_e32 v35, 0
	v_add_u32_e32 v87, v17, v22
	v_add_u32_e32 v88, v17, v23
	v_add_u32_e32 v89, v17, v89
	v_add_u32_e32 v90, v17, v90
	v_add_u32_e32 v91, v91, v92
	v_add_u32_e32 v92, v93, v92
	v_add_u32_e32 v93, v19, v20
	v_add_u32_e32 v94, v16, v18
	v_readlane_b32 s53, v252, 38
	v_readlane_b32 s54, v252, 39
	v_readlane_b32 s55, v252, 40
	v_readlane_b32 s56, v252, 41
	v_readlane_b32 s57, v252, 42
	v_readlane_b32 s58, v252, 43
	v_readlane_b32 s59, v252, 44
	v_readlane_b32 s64, v252, 49
	v_readlane_b32 s65, v252, 50
	v_readlane_b32 s66, v252, 51
	v_readlane_b32 s67, v252, 52
	v_and_b32_e32 v224, 7, v182
	v_lshrrev_b32_e32 v225, 6, v182
	v_and_b32_e32 v230, 3, v224
	v_xor_b32_e32 v226, v225, v230
	v_bfe_u32 v227, v182, 3, 3
	v_lshlrev_b32_e32 v227, 1, v227
	v_mul_u32_u24_e32 v228, 0x480, v224
	v_add3_u32 v227, v227, v228, 32
	v_lshl_add_u32 v91, v226, 4, v227
	v_add_u32_e32 v225, 4, v225
	v_xor_b32_e32 v226, v225, v230
	v_lshl_add_u32 v92, v226, 4, v227
	v_and_b32_e32 v224, 15, v182
	v_lshrrev_b32_e32 v225, 6, v182
	v_lshl_or_b32 v226, v225, 4, v224
	v_lshrrev_b32_e32 v228, 3, v226
	v_and_b32_e32 v228, 3, v228
	v_bfe_u32 v229, v182, 4, 2
	v_xor_b32_e32 v229, v229, v228
	v_mul_u32_u24_e32 v226, 0x90, v226
	v_add_u32_e32 v226, 32, v226
	v_lshl_add_u32 v68, v229, 4, v226
	s_nop 0
	s_nop 0
	s_nop 0
	s_nop 0
	s_nop 0
	s_nop 0
	s_nop 0
	s_nop 0
	s_nop 0
	s_nop 0
	s_nop 0
	s_nop 0
	s_nop 0
	s_nop 0
	s_nop 0
	s_nop 0
	s_nop 0
	s_nop 0
	s_nop 0
	s_nop 0
	s_nop 0
	s_nop 0
	s_nop 0
	s_nop 0
	s_nop 0
	s_nop 0
	s_nop 0
	s_nop 0
	s_nop 0
	s_nop 0
	s_nop 0
	s_nop 0

; template <int PROBE, int SONLY, int CPS>
; DI void ssd_chunk_loop(const Params& p, int layer, int b, int e, int c0, f32x4 (&h)[8], float& dtot, bool write_final) {
;     ...
;   u32x4 pc[4], pb[4], px[2];
;   u16 pru;
;   {
;     const int nb_ = b * 2048 + c0 * 64;
; #pragma unroll
;     for (int i = 0; i < 4; ++i) {
;       const int idx = tid + 256 * i, r = idx >> 4, c16 = idx & 15;
;       if (!SONLY) pc[i] = *(const u32x4*)(XBC + (size_t)(nb_ + r) * 1280 + 1024 + g * 128 + c16 * 8);
;       pb[i] = *(const u32x4*)(XBC + (size_t)(nb_ + r) * 1280 + 768 + g * 128 + c16 * 8);
;     }
; #pragma unroll
;     for (int i = 0; i < 2; ++i) {
;       const int idx = tid + 256 * i, r = idx >> 3, c8 = idx & 7;
;       px[i] = *(const u32x4*)(XBC + (size_t)(nb_ + r) * 1280 + e * 64 + c8 * 8);
;     }
;     pru = PROJ[(size_t)(nb_ + lane) * NPAD + C_DT + e];
;   }
.LBB0_508:
	s_mov_b64 s[0:1], -1
	s_and_b64 vcc, exec, s[8:9]
	s_cbranch_vccz .LBB0_558
	v_readlane_b32 s0, v255, 51
	s_add_i32 s2, s0, s15
	v_readlane_b32 s36, v252, 37
	s_and_b32 s8, s24, 0xff
	s_lshl_b64 s[6:7], s[2:3], 2
	v_readlane_b32 s44, v252, 45
	v_readlane_b32 s45, v252, 46
	s_add_u32 s0, s44, s6
	v_readlane_b32 s46, v252, 47
	s_addc_u32 s1, s45, s7
	v_readlane_b32 s37, v252, 38
	v_readlane_b32 s47, v252, 48
	s_add_u32 s36, s46, s6
	v_mov_b32_e32 v70, v182
	s_addc_u32 s37, s47, s7
	s_nop 0
	global_load_dword v71, v161, s[36:37]
	v_readlane_b32 s48, v252, 49
	v_readlane_b32 s49, v252, 50
	s_add_u32 s6, s48, s6
	v_readlane_b32 s80, v254, 18
	s_mul_i32 s2, s8, 0xab
	v_add_u32_e32 v39, 0x100, v70
	v_add_u32_e32 v40, 0x200, v70
	v_add_u32_e32 v41, 0x300, v70
	s_addc_u32 s7, s49, s7
	s_lshl_b32 s87, s25, 11
	v_readlane_b32 s81, v254, 19
	v_ashrrev_i32_e32 v175, 4, v70
	v_lshlrev_b32_e32 v38, 4, v70
	v_ashrrev_i32_e32 v177, 4, v39
	v_ashrrev_i32_e32 v178, 4, v40
	v_ashrrev_i32_e32 v179, 4, v41
	s_lshr_b32 s2, s2, 2
	global_load_dword v128, v161, s[6:7]
	global_load_dword v181, v161, s[0:1]
	s_or_b32 s1, s87, 0x500
	v_mov_b64_e32 v[32:33], s[80:81]
	v_and_b32_e32 v133, 63, v70
	v_lshlrev_b32_e32 v34, 3, v70
	v_and_b32_e32 v160, 0xf0, v38
	s_lshl_b32 s22, s15, 6
	s_lshl_b32 s9, s15, 7
	s_and_b32 s2, s2, 0x3f00
	v_add_u32_e32 v38, s1, v175
	v_add_u32_e32 v40, s1, v177
	v_add_u32_e32 v42, s1, v178
	v_add_u32_e32 v44, s1, v179
	v_mov_b64_e32 v[36:37], s[4:5]
	v_ashrrev_i32_e32 v176, 3, v70
	v_and_b32_e32 v74, 56, v34
	v_ashrrev_i32_e32 v180, 3, v39
	s_add_u32 s0, s80, s9
	v_or_b32_e32 v45, s1, v133
	v_mad_i64_i32 v[38:39], s[6:7], v38, s34, v[32:33]
	v_mad_i64_i32 v[40:41], s[6:7], v40, s34, v[32:33]
	v_mad_i64_i32 v[42:43], s[6:7], v42, s34, v[32:33]
	v_mad_i64_i32 v[32:33], s[6:7], v44, s34, v[32:33]
	v_mov_b32_e32 v35, v161
	s_mov_b32 s37, s3
	v_lshlrev_b32_e32 v34, 1, v74
	v_add_u32_e32 v46, s1, v176
	v_add_u32_e32 v47, s1, v180
	s_addc_u32 s1, s81, 0
	v_mad_u64_u32 v[36:37], s[6:7], v45, s97, v[36:37]
	s_lshl_b32 s36, s8, 1
	v_lshl_add_u64 v[38:39], v[38:39], 0, s[2:3]
	v_lshl_add_u64 v[40:41], v[40:41], 0, s[2:3]
	v_lshl_add_u64 v[42:43], v[42:43], 0, s[2:3]
	v_lshl_add_u64 v[32:33], v[32:33], 0, s[2:3]
	v_lshl_add_u64 v[130:131], s[0:1], 0, v[34:35]
	v_lshl_add_u64 v[64:65], v[36:37], 0, s[36:37]
	v_lshl_add_u64 v[36:37], v[38:39], 0, v[160:161]
	v_lshl_add_u64 v[44:45], v[40:41], 0, v[160:161]
	v_lshl_add_u64 v[52:53], v[42:43], 0, v[160:161]
	v_lshl_add_u64 v[60:61], v[32:33], 0, v[160:161]
	v_mad_i64_i32 v[66:67], s[6:7], v46, s34, v[130:131]
	v_mad_i64_i32 v[68:69], s[6:7], v47, s34, v[130:131]
	global_load_dwordx4 v[32:35], v[36:37], off offset:2048
	s_nop 0
	global_load_dwordx4 v[36:39], v[36:37], off offset:1536
	s_nop 0
	global_load_dwordx4 v[40:43], v[44:45], off offset:2048
	s_nop 0
	global_load_dwordx4 v[44:47], v[44:45], off offset:1536
	s_nop 0
	global_load_dwordx4 v[48:51], v[52:53], off offset:2048
	s_nop 0
	global_load_dwordx4 v[52:55], v[52:53], off offset:1536
	s_nop 0
	global_load_dwordx4 v[56:59], v[60:61], off offset:2048
	s_nop 0
	global_load_dwordx4 v[60:63], v[60:61], off offset:1536
	s_nop 0
	global_load_dwordx4 v[108:111], v[66:67], off
	global_load_dwordx4 v[104:107], v[68:69], off
	v_add_co_u32_e32 v64, vcc, s16, v64
	v_ashrrev_i32_e32 v72, 6, v70
	s_nop 0
	v_addc_co_u32_e32 v65, vcc, 0, v65, vcc
	global_load_ushort v163, v[64:65], off offset:1536
	v_and_b32_e32 v73, 15, v70
	v_lshlrev_b32_e32 v65, 4, v72
	s_movk_i32 s9, 0x110
	v_or_b32_e32 v132, v65, v73
	v_and_b32_e32 v68, 48, v70
	s_waitcnt vmcnt(13)
; DI f32x4 mfma16(bf16x8 a, bf16x8 b, f32x4 c) { return __builtin_amdgcn_mfma_f32_16x16x32_bf16(a, b, c, 0, 0, 0); }
; template <int PROBE, int SONLY, int CPS>
; DI void ssd_chunk_loop(const Params& p, int layer, int b, int e, int c0, f32x4 (&h)[8], float& dtot, bool write_final) {
;     ...
;     for (int i = 0; i < 2; ++i) {
;       const int idx = tid + 256 * i, r = idx >> 3, c8 = idx & 7;
;       const float dtv = dt_s[r];
;       float f[8]; unpack8v(xr[i], f);
; #pragma unroll
;       for (int j = 0; j < 8; ++j) Xt[(c8 * 8 + j) * 72 + r] = f2bf(f[j] * dtv);
;     }
;     ...
;         if (ks == 0 || qt >= 2) y[qt] = mfma16(ldfrag(Xt, 72, w * 16, ks * 32, lane), ldfrag(Ms, 72, qt * 16, ks * 32, lane), y[qt]);
;     ...
;         const bf16x8 xf = ldfrag(Xt, 72, w * 16, ks * 32, lane);
	v_mul_f32_e32 v66, 0x3fb8aa3b, v71
	v_exp_f32_e32 v204, v66
	v_lshrrev_b32_e32 v66, 2, v70
	v_and_b32_e32 v203, 12, v66
	v_or_b32_e32 v134, v203, v65
	v_mul_lo_u32 v65, v132, s9
	v_add_u32_e32 v65, 32, v65
	v_lshlrev_b32_e32 v69, 7, v132
	v_add_u32_e32 v209, v65, v68
	v_sub_u32_e32 v65, v65, v69
	v_and_b32_e32 v76, 64, v190
	v_add_u32_e32 v210, 32, v68
	v_add_u32_e32 v212, v65, v68
	v_xor_b32_e32 v68, 16, v190
	v_add_u32_e32 v77, 64, v76
	v_ashrrev_i32_e32 v135, 31, v134
	v_cmp_lt_i32_e32 vcc, v68, v77
	v_lshl_add_u64 v[136:137], v[134:135], 1, s[0:1]
	s_lshl_b32 s0, s8, 2
	v_cndmask_b32_e32 v68, v190, v68, vcc
	v_readlane_b32 s6, v254, 22
	v_add_u32_e32 v64, 32, v160
	v_lshlrev_b32_e32 v213, 2, v68
	v_xor_b32_e32 v68, 32, v190
	v_readlane_b32 s7, v254, 23
	s_add_u32 s0, s6, s0
	v_cmp_lt_i32_e32 vcc, v68, v77
	s_addc_u32 s1, s7, 0
	v_mad_u64_u32 v[138:139], s[6:7], v175, s9, v[64:65]
	v_mad_u64_u32 v[140:141], s[6:7], v177, s9, v[64:65]
	v_mad_u64_u32 v[142:143], s[6:7], v178, s9, v[64:65]
	v_mad_u64_u32 v[144:145], s[6:7], v179, s9, v[64:65]
	v_add_u32_e32 v64, -1, v190
	v_cndmask_b32_e32 v68, v190, v68, vcc
	v_cmp_lt_i32_e32 vcc, v64, v76
	v_lshlrev_b32_e32 v69, 1, v203
	v_add_u32_e32 v227, v65, v69
	v_cndmask_b32_e32 v64, v64, v190, vcc
	v_lshlrev_b32_e32 v139, 2, v64
	v_add_u32_e32 v64, -2, v190
	v_cmp_lt_i32_e32 vcc, v64, v76
	v_or_b32_e32 v65, 16, v203
	v_cmp_le_i32_e64 s[60:61], v65, v132
	v_cndmask_b32_e32 v64, v64, v190, vcc
	v_lshlrev_b32_e32 v141, 2, v64
	v_add_u32_e32 v64, -4, v190
	v_cmp_lt_i32_e32 vcc, v64, v76
	v_lshl_add_u32 v228, v65, 2, s17
	v_or_b32_e32 v65, 17, v203
	v_cndmask_b32_e32 v64, v64, v190, vcc
	v_lshlrev_b32_e32 v143, 2, v64
	v_add_u32_e32 v64, -8, v190
	v_cmp_lt_i32_e32 vcc, v64, v76
	v_cmp_le_i32_e64 s[62:63], v65, v132
	v_lshl_add_u32 v229, v65, 2, s17
	v_or_b32_e32 v65, 18, v203
	v_cndmask_b32_e32 v64, v64, v190, vcc
	v_cmp_le_i32_e64 s[64:65], v65, v132
	v_lshl_add_u32 v230, v65, 2, s17
	v_or_b32_e32 v65, 19, v203
	v_lshlrev_b32_e32 v145, 2, v64
	v_add_u32_e32 v64, -16, v190
	v_cmp_le_i32_e64 s[66:67], v65, v132
	v_lshl_add_u32 v231, v65, 2, s17
	v_or_b32_e32 v65, 32, v203
	v_cmp_lt_i32_e32 vcc, v64, v76
	s_movk_i32 s6, 0x1200
	v_cmp_le_i32_e64 s[68:69], v65, v132
	v_lshl_add_u32 v232, v65, 2, s17
	v_or_b32_e32 v65, 33, v203
	v_mad_u32_u24 v206, v133, s9, 32
	v_mul_i32_i24_e32 v67, 0xfffffef2, v133
	v_cndmask_b32_e32 v64, v64, v190, vcc
	v_mul_lo_u32 v72, v72, s6
	v_cmp_le_i32_e64 s[70:71], v65, v132
	v_lshl_add_u32 v233, v65, 2, s17
	v_or_b32_e32 v65, 34, v203
	v_lshlrev_b32_e32 v217, 2, v64
	v_subrev_u32_e32 v64, 32, v190
	v_add3_u32 v221, v206, v67, v72
	v_lshlrev_b32_e32 v67, 1, v133
	v_cmp_le_i32_e64 s[72:73], v65, v132
	v_lshl_add_u32 v234, v65, 2, s17
	v_or_b32_e32 v65, 35, v203
	v_cmp_lt_i32_e32 vcc, v64, v76
	v_add3_u32 v222, 32, v72, v67
	v_or_b32_e32 v67, 2, v203
	v_cmp_le_i32_e64 s[74:75], v65, v132
	v_lshl_add_u32 v235, v65, 2, s17
	v_or_b32_e32 v65, 48, v203
	v_lshlrev_b32_e32 v66, 2, v133
	v_and_b32_e32 v207, 0xffffffc0, v70
	v_readlane_b32 s13, v255, 27
	v_cndmask_b32_e32 v64, v64, v190, vcc
	v_cmp_le_i32_e64 s[56:57], v67, v132
	v_lshl_add_u32 v225, v67, 2, s17
	v_or_b32_e32 v67, 3, v203
	v_cmp_le_i32_e64 s[76:77], v65, v132
	v_lshl_add_u32 v236, v65, 2, s17
	v_or_b32_e32 v65, 49, v203
	s_add_u32 s6, s80, s2
	v_readlane_b32 s38, v252, 39
	v_readlane_b32 s39, v252, 40
	v_readlane_b32 s40, v252, 41
	v_readlane_b32 s41, v252, 42
	v_readlane_b32 s42, v252, 43
	v_readlane_b32 s43, v252, 44
	v_readlane_b32 s50, v252, 51
	v_readlane_b32 s51, v252, 52
	v_add_u32_e32 v205, s17, v66
	v_add_u32_e32 v71, 32, v69
	v_lshlrev_b32_e32 v75, 2, v73
	v_lshlrev_b32_e32 v214, 2, v68
	v_lshlrev_b32_e32 v68, 2, v207
	v_add_u32_e32 v215, s13, v66
	v_readlane_b32 s82, v255, 28
	v_lshlrev_b32_e32 v218, 2, v64
	v_lshl_add_u32 v64, v176, 1, 32
	v_mul_u32_u24_e32 v66, 0x90, v74
	v_lshl_add_u32 v74, v180, 1, 32
	v_mul_u32_u24_e32 v223, 0x110, v73
	v_cmp_le_i32_e64 s[58:59], v67, v132
	v_lshl_add_u32 v226, v67, 2, s17
	v_cmp_le_i32_e64 s[78:79], v65, v132
	v_lshl_add_u32 v237, v65, 2, s17
	v_or_b32_e32 v96, 50, v203
	v_or_b32_e32 v97, 51, v203
	v_mul_u32_u24_e32 v65, 0x90, v73
	v_mad_u32_u24 v67, v73, s11, v199
	s_addc_u32 s7, s81, 0
	v_cmp_gt_u32_e64 s[36:37], 64, v70
	v_lshl_add_u32 v208, v132, 2, s17
	v_add_u32_e32 v211, s17, v75
	v_cmp_gt_u32_e64 s[38:39], 16, v133
	v_cmp_gt_i32_e64 s[40:41], 64, v70
	v_lshl_add_u32 v216, v70, 2, s82
	v_cmp_eq_u32_e64 s[42:43], 0, v133
	v_cmp_gt_u32_e64 s[44:45], 2, v133
	v_cmp_gt_u32_e64 s[46:47], 4, v133
	v_cmp_gt_u32_e64 s[48:49], 8, v133
	v_cmp_gt_u32_e64 s[50:51], 32, v133
	v_lshl_add_u32 v219, v176, 2, s13
	v_lshl_add_u32 v220, v180, 2, s13
	v_cmp_le_i32_e64 s[52:53], v203, v132
	v_lshl_add_u32 v224, v203, 2, s17
	v_cmp_lt_i32_e64 s[54:55], v203, v132
	v_lshl_add_u32 v238, v96, 2, s17
	v_lshl_add_u32 v239, v97, 2, s17
	v_add3_u32 v240, s82, v68, v75
	s_waitcnt vmcnt(12)
	v_mov_b32_e32 v129, v128
	v_lshl_add_u64 v[146:147], s[6:7], 0, v[160:161]
	v_add_u32_e32 v241, s87, v70
	v_or_b32_e32 v242, s87, v73
	s_movk_i32 s13, 0x540
	s_lshl_b32 s8, s8, 1
	v_add_u32_e32 v243, v64, v66
	v_add_u32_e32 v244, v74, v66
	v_add_u32_e32 v245, v71, v223
	v_add_u32_e32 v246, v210, v65
	v_add_u32_e32 v247, v210, v67
	v_mov_b32_e32 v64, v0
	v_mov_b32_e32 v65, v1
	v_mov_b32_e32 v66, v2
	v_mov_b32_e32 v67, v3
	v_mov_b32_e32 v68, v4
	v_mov_b32_e32 v69, v5
	v_mov_b32_e32 v70, v6
	v_mov_b32_e32 v71, v7
	v_mov_b32_e32 v72, v8
	v_mov_b32_e32 v73, v9
	v_mov_b32_e32 v74, v10
	v_mov_b32_e32 v75, v11
	v_mov_b32_e32 v76, v12
	v_mov_b32_e32 v77, v13
	v_mov_b32_e32 v78, v14
	v_mov_b32_e32 v79, v15
	v_mov_b32_e32 v80, v16
	v_mov_b32_e32 v81, v17
	v_mov_b32_e32 v82, v18
	v_mov_b32_e32 v83, v19
	v_mov_b32_e32 v84, v20
	v_mov_b32_e32 v85, v21
	v_mov_b32_e32 v86, v22
	v_mov_b32_e32 v87, v23
	v_mov_b32_e32 v88, v24
	v_mov_b32_e32 v89, v25
	v_mov_b32_e32 v90, v26
	v_mov_b32_e32 v91, v27
	v_mov_b32_e32 v92, v28
	v_mov_b32_e32 v93, v29
	v_mov_b32_e32 v94, v30
	v_mov_b32_e32 v95, v31
	v_cmp_le_i32_e64 s[80:81], v96, v132
	v_cmp_le_i32_e64 s[82:83], v97, v132
	v_and_b32_e32 v0, 7, v182
	v_lshrrev_b32_e32 v1, 6, v182
	v_and_b32_e32 v6, 3, v0
	v_xor_b32_e32 v2, v1, v6
	v_bfe_u32 v3, v182, 3, 3
	v_lshlrev_b32_e32 v3, 1, v3
	v_mul_u32_u24_e32 v4, 0x480, v0
	v_add3_u32 v3, v3, v4, 32
	v_lshl_add_u32 v243, v2, 4, v3
	v_add_u32_e32 v1, 4, v1
	v_xor_b32_e32 v2, v1, v6
	v_lshl_add_u32 v244, v2, 4, v3
	v_and_b32_e32 v0, 15, v182
	v_lshrrev_b32_e32 v1, 6, v182
	v_lshl_or_b32 v2, v1, 4, v0
	v_lshrrev_b32_e32 v4, 3, v2
	v_and_b32_e32 v4, 3, v4
	v_bfe_u32 v5, v182, 4, 2
	v_xor_b32_e32 v5, v5, v4
	v_mul_u32_u24_e32 v2, 0x90, v2
	v_add_u32_e32 v2, 32, v2
	v_lshl_add_u32 v212, v5, 4, v2
	s_branch .LBB0_511

; template <int PROBE, int SONLY, int CPS>
; DI void ssd_chunk_loop(const Params& p, int layer, int b, int e, int c0, f32x4 (&h)[8], float& dtot, bool write_final) {
;     ...
;   u32x4 pc[4], pb[4], px[2];
;   u16 pru;
;   {
;     const int nb_ = b * 2048 + c0 * 64;
; #pragma unroll
;     for (int i = 0; i < 4; ++i) {
;       const int idx = tid + 256 * i, r = idx >> 4, c16 = idx & 15;
;       if (!SONLY) pc[i] = *(const u32x4*)(XBC + (size_t)(nb_ + r) * 1280 + 1024 + g * 128 + c16 * 8);
;       pb[i] = *(const u32x4*)(XBC + (size_t)(nb_ + r) * 1280 + 768 + g * 128 + c16 * 8);
;     }
; #pragma unroll
;     for (int i = 0; i < 2; ++i) {
;       const int idx = tid + 256 * i, r = idx >> 3, c8 = idx & 7;
;       px[i] = *(const u32x4*)(XBC + (size_t)(nb_ + r) * 1280 + e * 64 + c8 * 8);
;     }
;     pru = PROJ[(size_t)(nb_ + lane) * NPAD + C_DT + e];
;   }
.LBB0_561:
	s_or_b64 exec, exec, s[0:1]
	s_bfe_i32 s0, s24, 0x80000
	s_mul_i32 s0, s0, 43
	s_bfe_u32 s1, s0, 0x1000f
	s_bfe_u32 s0, s0, 0x80008
	s_add_i32 s2, s0, s1
	v_readlane_b32 s0, v255, 51
	s_add_i32 s0, s0, s15
	s_ashr_i32 s1, s0, 31
	v_readlane_b32 s36, v252, 37
	s_lshl_b64 s[0:1], s[0:1], 2
	v_readlane_b32 s44, v252, 45
	v_readlane_b32 s45, v252, 46
	s_add_u32 s6, s44, s0
	v_readlane_b32 s46, v252, 47
	s_addc_u32 s7, s45, s1
	v_readlane_b32 s47, v252, 48
	s_add_u32 s8, s46, s0
	v_mov_b32_e32 v70, v182
	s_addc_u32 s9, s47, s1
	global_load_dword v65, v161, s[8:9]
	v_readlane_b32 s48, v252, 49
	v_readlane_b32 s49, v252, 50
	s_add_u32 s8, s48, s0
	v_readlane_b32 s78, v254, 18
	v_add_u32_e32 v37, 0x100, v70
	v_add_u32_e32 v38, 0x200, v70
	v_add_u32_e32 v39, 0x300, v70
	s_sext_i32_i8 s13, s2
	s_addc_u32 s9, s49, s1
	s_lshl_b32 s2, s25, 11
	v_readlane_b32 s79, v254, 19
	v_ashrrev_i32_e32 v143, 4, v70
	v_lshlrev_b32_e32 v36, 4, v70
	v_ashrrev_i32_e32 v145, 4, v37
	v_ashrrev_i32_e32 v146, 4, v38
	v_ashrrev_i32_e32 v147, 4, v39
	s_lshl_b32 s22, s13, 7
	s_lshl_b32 s0, s15, 6
	global_load_dword v96, v161, s[8:9]
	global_load_dword v149, v161, s[6:7]
	s_add_i32 s6, s2, s21
	v_mov_b64_e32 v[32:33], s[78:79]
	v_and_b32_e32 v160, 0xf0, v36
	s_ashr_i32 s23, s22, 31
	s_ashr_i32 s1, s0, 31
	v_add_u32_e32 v36, s6, v143
	v_add_u32_e32 v38, s6, v145
	v_add_u32_e32 v40, s6, v146
	v_add_u32_e32 v42, s6, v147
	v_lshlrev_b32_e32 v34, 3, v70
	v_ashrrev_i32_e32 v148, 3, v37
	s_lshl_b64 s[8:9], s[22:23], 1
	s_lshl_b64 s[86:87], s[0:1], 1
	v_mad_i64_i32 v[36:37], s[22:23], v36, s34, v[32:33]
	v_mad_i64_i32 v[38:39], s[22:23], v38, s34, v[32:33]
	v_mad_i64_i32 v[40:41], s[22:23], v40, s34, v[32:33]
	v_mad_i64_i32 v[32:33], s[22:23], v42, s34, v[32:33]
	v_and_b32_e32 v81, 56, v34
	s_add_u32 s22, s78, s86
	v_lshl_add_u64 v[36:37], v[36:37], 0, s[8:9]
	v_lshl_add_u64 v[38:39], v[38:39], 0, s[8:9]
	v_lshl_add_u64 v[40:41], v[40:41], 0, s[8:9]
	v_lshl_add_u64 v[32:33], v[32:33], 0, s[8:9]
	v_mov_b32_e32 v35, v161
	v_lshlrev_b32_e32 v34, 1, v81
	s_addc_u32 s23, s79, s87
	v_lshl_add_u64 v[36:37], v[36:37], 0, v[160:161]
	v_lshl_add_u64 v[44:45], v[38:39], 0, v[160:161]
	v_lshl_add_u64 v[52:53], v[40:41], 0, v[160:161]
	v_lshl_add_u64 v[60:61], v[32:33], 0, v[160:161]
	v_mov_b32_e32 v64, s24
	v_and_b32_e32 v142, 63, v70
	v_lshl_add_u64 v[98:99], s[22:23], 0, v[34:35]
	global_load_dwordx4 v[32:35], v[36:37], off offset:2048
	s_nop 0
	global_load_dwordx4 v[36:39], v[36:37], off offset:1536
	s_nop 0
	global_load_dwordx4 v[40:43], v[44:45], off offset:2048
	s_nop 0
	global_load_dwordx4 v[44:47], v[44:45], off offset:1536
	s_nop 0
	global_load_dwordx4 v[48:51], v[52:53], off offset:2048
	s_nop 0
	global_load_dwordx4 v[52:55], v[52:53], off offset:1536
	s_nop 0
	global_load_dwordx4 v[56:59], v[60:61], off offset:2048
	s_nop 0
	global_load_dwordx4 v[60:63], v[60:61], off offset:1536
	v_or_b32_e32 v82, s6, v142
	v_bfe_i32 v100, v64, 0, 8
	v_ashrrev_i32_e32 v101, 31, v100
	v_ashrrev_i32_e32 v144, 3, v70
	v_add_u32_e32 v66, s6, v144
	v_add_u32_e32 v68, s6, v148
	v_mad_i64_i32 v[66:67], s[24:25], v66, s34, v[98:99]
	v_mad_i64_i32 v[68:69], s[24:25], v68, s34, v[98:99]
	global_load_dwordx4 v[76:79], v[66:67], off
	global_load_dwordx4 v[72:75], v[68:69], off
	v_ashrrev_i32_e32 v71, 6, v70
	v_lshrrev_b32_e32 v66, 2, v70
	v_and_b32_e32 v80, 15, v70
	v_and_b32_e32 v68, 12, v66
	s_movk_i32 s7, 0x110
	v_and_b32_e32 v67, 48, v70
	v_and_b32_e32 v87, 64, v190
	v_add_u32_e32 v156, 32, v67
	v_lshlrev_b32_e32 v69, 2, v142
	v_mad_u32_u24 v152, v142, s7, 32
	v_readlane_b32 s13, v255, 27
	s_waitcnt vmcnt(12)
; DI f32x4 mfma16(bf16x8 a, bf16x8 b, f32x4 c) { return __builtin_amdgcn_mfma_f32_16x16x32_bf16(a, b, c, 0, 0, 0); }
; template <int PROBE, int SONLY, int CPS>
; DI void ssd_chunk_loop(const Params& p, int layer, int b, int e, int c0, f32x4 (&h)[8], float& dtot, bool write_final) {
;     ...
;     for (int i = 0; i < 2; ++i) {
;       const int idx = tid + 256 * i, r = idx >> 3, c8 = idx & 7;
;       const float dtv = dt_s[r];
;       float f[8]; unpack8v(xr[i], f);
; #pragma unroll
;       for (int j = 0; j < 8; ++j) Xt[(c8 * 8 + j) * 72 + r] = f2bf(f[j] * dtv);
;     }
;     ...
;         if (ks == 0 || qt >= 2) y[qt] = mfma16(ldfrag(Xt, 72, w * 16, ks * 32, lane), ldfrag(Ms, 72, qt * 16, ks * 32, lane), y[qt]);
;     ...
;         const bf16x8 xf = ldfrag(Xt, 72, w * 16, ks * 32, lane);
	v_mul_f32_e32 v65, 0x3fb8aa3b, v65
	v_exp_f32_e32 v150, v65
	v_mov_b64_e32 v[64:65], s[4:5]
	v_mad_i64_i32 v[64:65], s[24:25], v82, s97, v[64:65]
	v_lshl_add_u64 v[64:65], v[100:101], 1, v[64:65]
	v_add_co_u32_e32 v64, vcc, s16, v64
	v_add_u32_e32 v151, s17, v69
	s_nop 0
	v_addc_co_u32_e32 v65, vcc, 0, v65, vcc
	global_load_ushort v163, v[64:65], off offset:1536
	v_lshlrev_b32_e32 v65, 4, v71
	v_or_b32_e32 v102, v68, v65
	v_or_b32_e32 v65, v65, v80
	v_mul_lo_u32 v66, v65, s7
	v_add_u32_e32 v66, 32, v66
	v_lshlrev_b32_e32 v83, 7, v65
	v_sub_u32_e32 v83, v66, v83
	v_add_u32_e32 v155, v66, v67
	v_add_u32_e32 v158, v83, v67
	v_xor_b32_e32 v66, 16, v190
	v_add_u32_e32 v67, 64, v87
	v_cmp_lt_i32_e32 vcc, v66, v67
	v_ashrrev_i32_e32 v103, 31, v102
	v_lshl_add_u64 v[104:105], v[102:103], 1, s[22:23]
	v_cndmask_b32_e32 v66, v190, v66, vcc
	v_lshlrev_b32_e32 v159, 2, v66
	v_xor_b32_e32 v66, 32, v190
	v_cmp_lt_i32_e32 vcc, v66, v67
	v_readlane_b32 s22, v254, 22
	v_add_u32_e32 v64, 32, v160
	v_cndmask_b32_e32 v66, v190, v66, vcc
	v_lshlrev_b32_e32 v164, 2, v66
	v_lshlrev_b64 v[66:67], 2, v[100:101]
	v_readlane_b32 s23, v254, 23
	v_mul_i32_i24_e32 v82, 0xfffffef2, v142
	v_add_u32_e32 v165, s13, v69
	v_lshl_add_u64 v[106:107], s[22:23], 0, v[66:67]
	v_mad_u64_u32 v[108:109], s[22:23], v143, s7, v[64:65]
	v_mad_u64_u32 v[110:111], s[22:23], v145, s7, v[64:65]
	v_mad_u64_u32 v[112:113], s[22:23], v146, s7, v[64:65]
	v_mad_u64_u32 v[114:115], s[22:23], v147, s7, v[64:65]
	v_add_u32_e32 v64, -1, v190
	v_cmp_lt_i32_e32 vcc, v64, v87
	s_movk_i32 s7, 0x1200
	v_mul_lo_u32 v69, v71, s7
	v_cndmask_b32_e32 v64, v64, v190, vcc
	v_lshlrev_b32_e32 v109, 2, v64
	v_add_u32_e32 v64, -2, v190
	v_cmp_lt_i32_e32 vcc, v64, v87
	v_lshlrev_b32_e32 v71, 1, v142
	v_add3_u32 v171, v152, v82, v69
	v_cndmask_b32_e32 v64, v64, v190, vcc
	v_add3_u32 v172, 32, v69, v71
	v_or_b32_e32 v69, 2, v68
	v_lshlrev_b32_e32 v111, 2, v64
	v_add_u32_e32 v64, -4, v190
	v_cmp_le_i32_e64 s[56:57], v69, v65
	v_lshl_add_u32 v175, v69, 2, s17
	v_or_b32_e32 v69, 3, v68
	v_cmp_lt_i32_e32 vcc, v64, v87
	v_cmp_le_i32_e64 s[58:59], v69, v65
	v_lshl_add_u32 v176, v69, 2, s17
	v_or_b32_e32 v69, 16, v68
	v_cndmask_b32_e32 v64, v64, v190, vcc
	v_cmp_le_i32_e64 s[60:61], v69, v65
	v_lshl_add_u32 v178, v69, 2, s17
	v_or_b32_e32 v69, 17, v68
	v_lshlrev_b32_e32 v113, 2, v64
	v_add_u32_e32 v64, -8, v190
	v_cmp_le_i32_e64 s[62:63], v69, v65
	v_lshl_add_u32 v179, v69, 2, s17
	v_or_b32_e32 v69, 18, v68
	v_cmp_lt_i32_e32 vcc, v64, v87
	v_cmp_le_i32_e64 s[64:65], v69, v65
	v_lshl_add_u32 v180, v69, 2, s17
	v_or_b32_e32 v69, 19, v68
	v_cndmask_b32_e32 v64, v64, v190, vcc
	v_cmp_le_i32_e64 s[66:67], v69, v65
	v_lshl_add_u32 v181, v69, 2, s17
	v_or_b32_e32 v69, 32, v68
	v_lshlrev_b32_e32 v115, 2, v64
	v_add_u32_e32 v64, -16, v190
	v_cmp_le_i32_e64 s[68:69], v69, v65
	v_lshl_add_u32 v203, v69, 2, s17
	v_or_b32_e32 v69, 33, v68
	v_cmp_lt_i32_e32 vcc, v64, v87
	v_cmp_le_i32_e64 s[70:71], v69, v65
	v_lshl_add_u32 v204, v69, 2, s17
	v_or_b32_e32 v69, 34, v68
	v_cndmask_b32_e32 v64, v64, v190, vcc
	v_cmp_le_i32_e64 s[72:73], v69, v65
	v_lshl_add_u32 v205, v69, 2, s17
	v_or_b32_e32 v69, 35, v68
	s_add_i32 s18, s19, 10
	v_lshlrev_b32_e32 v167, 2, v64
	v_subrev_u32_e32 v64, 32, v190
	v_cmp_le_i32_e64 s[74:75], v69, v65
	v_lshl_add_u32 v206, v69, 2, s17
	v_or_b32_e32 v69, 48, v68
	v_cmp_lt_i32_e32 vcc, v64, v87
	v_cmp_le_i32_e64 s[76:77], v69, v65
	v_lshl_add_u32 v207, v69, 2, s17
	v_or_b32_e32 v69, 49, v68
	s_add_u32 s8, s78, s8
	v_and_b32_e32 v153, 0xffffffc0, v70
	v_lshlrev_b32_e32 v84, 1, v68
	v_cndmask_b32_e32 v64, v64, v190, vcc
	v_cmp_le_i32_e64 s[52:53], v68, v65
	v_lshl_add_u32 v174, v68, 2, s17
	v_cmp_lt_i32_e64 s[54:55], v68, v65
	s_addc_u32 s9, s79, s9
	v_cmp_le_i32_e64 s[78:79], v69, v65
	v_lshl_add_u32 v208, v69, 2, s17
	v_or_b32_e32 v69, 50, v68
	v_or_b32_e32 v68, 51, v68
	v_readlane_b32 s37, v252, 38
	v_readlane_b32 s38, v252, 39
	v_readlane_b32 s39, v252, 40
	v_readlane_b32 s40, v252, 41
	v_readlane_b32 s41, v252, 42
	v_readlane_b32 s42, v252, 43
	v_readlane_b32 s43, v252, 44
	v_readlane_b32 s50, v252, 51
	v_readlane_b32 s51, v252, 52
	v_lshl_add_u32 v154, v65, 2, s17
	v_add_u32_e32 v85, 32, v84
	v_lshlrev_b32_e32 v86, 2, v80
	v_lshlrev_b32_e32 v88, 2, v153
	v_readlane_b32 s21, v255, 28
	v_lshlrev_b32_e32 v168, 2, v64
	v_lshl_add_u32 v64, v144, 1, 32
	v_mul_u32_u24_e32 v66, 0x90, v81
	v_lshl_add_u32 v67, v148, 1, 32
	v_mul_u32_u24_e32 v173, 0x110, v80
	v_cmp_le_i32_e64 s[80:81], v69, v65
	v_cmp_le_i32_e64 s[82:83], v68, v65
	v_lshl_add_u32 v211, v68, 2, s17
	v_mul_u32_u24_e32 v65, 0x90, v80
	v_mad_u32_u24 v68, v80, s11, v199
	s_mov_b32 s15, 0
	v_cmp_gt_u32_e64 s[36:37], 64, v70
	v_add_u32_e32 v157, s17, v86
	v_cmp_gt_u32_e64 s[38:39], 16, v142
	v_cmp_gt_i32_e64 s[40:41], 64, v70
	v_lshl_add_u32 v166, v70, 2, s21
	v_cmp_eq_u32_e64 s[42:43], 0, v142
	v_cmp_gt_u32_e64 s[44:45], 2, v142
	v_cmp_gt_u32_e64 s[46:47], 4, v142
	v_cmp_gt_u32_e64 s[48:49], 8, v142
	v_cmp_gt_u32_e64 s[50:51], 32, v142
	v_lshl_add_u32 v169, v144, 2, s13
	v_lshl_add_u32 v170, v148, 2, s13
	v_add_u32_e32 v177, v83, v84
	v_lshl_add_u64 v[116:117], s[8:9], 0, v[160:161]
	v_lshl_add_u32 v160, v69, 2, s17
	v_add_u32_e32 v209, s6, v70
	v_or_b32_e32 v210, s6, v80
	v_add3_u32 v212, s21, v88, v86
	s_waitcnt vmcnt(12)
	v_mov_b32_e32 v97, v96
	v_add_u32_e32 v213, v64, v66
	v_add_u32_e32 v214, v67, v66
	v_add_u32_e32 v215, v85, v173
	v_add_u32_e32 v216, v156, v65
	v_add_u32_e32 v217, v156, v68
	v_and_b32_e32 v224, 7, v182
	v_lshrrev_b32_e32 v225, 6, v182
	v_and_b32_e32 v230, 3, v224
	v_xor_b32_e32 v226, v225, v230
	v_bfe_u32 v227, v182, 3, 3
	v_lshlrev_b32_e32 v227, 1, v227
	v_mul_u32_u24_e32 v228, 0x480, v224
	v_add3_u32 v227, v227, v228, 32
	v_lshl_add_u32 v213, v226, 4, v227
	v_add_u32_e32 v225, 4, v225
	v_xor_b32_e32 v226, v225, v230
	v_lshl_add_u32 v214, v226, 4, v227
	v_and_b32_e32 v224, 15, v182
	v_lshrrev_b32_e32 v225, 6, v182
	v_lshl_or_b32 v226, v225, 4, v224
	v_lshrrev_b32_e32 v228, 3, v226
	v_and_b32_e32 v228, 3, v228
	v_bfe_u32 v229, v182, 4, 2
	v_xor_b32_e32 v229, v229, v228
	v_mul_u32_u24_e32 v226, 0x90, v226
	v_add_u32_e32 v226, 32, v226
	v_lshl_add_u32 v158, v229, 4, v226
	s_branch .LBB0_563
